# full stack + all GEMM K-loop heads (and the attention unit loop) aligned to 64 bytes
# speedup vs baseline: 1.0035x; 1.0035x over previous
.LBB0_114:
	s_ashr_i32 s35, s34, 31
	s_lshl_b64 s[38:39], s[34:35], 21
	s_add_u32 s38, s8, s38
	s_addc_u32 s39, s9, s39
	s_and_b64 s[40:41], s[6:7], exec
	s_cselect_b32 s35, s39, s45
	s_cselect_b32 s43, s38, s44
	s_ashr_i32 s37, s36, 31
	s_lshl_b64 s[40:41], s[36:37], 21
	s_add_u32 s40, s25, s40
	s_addc_u32 s41, s50, s41
	s_and_b64 s[48:49], s[6:7], exec
	s_cselect_b32 s37, s41, s47
	s_cselect_b32 s66, s40, s46
	s_add_u32 s44, s44, 0x100080
	s_addc_u32 s45, s45, 0
	s_add_u32 s67, s46, 0x100
	v_mov_b32_e32 v2, 0
	s_addc_u32 s68, s47, 0
	s_mov_b32 s69, -2
	v_mov_b32_e32 v3, v2
	v_mov_b32_e32 v4, v2
	v_mov_b32_e32 v5, v2
	v_mov_b32_e32 v6, v2
	v_mov_b32_e32 v7, v2
	v_mov_b32_e32 v8, v2
	v_mov_b32_e32 v9, v2
	v_mov_b32_e32 v10, v2
	v_mov_b32_e32 v11, v2
	v_mov_b32_e32 v12, v2
	v_mov_b32_e32 v13, v2
	v_mov_b32_e32 v18, v2
	v_mov_b32_e32 v19, v2
	v_mov_b32_e32 v20, v2
	v_mov_b32_e32 v21, v2
	v_mov_b32_e32 v26, v2
	v_mov_b32_e32 v27, v2
	v_mov_b32_e32 v28, v2
	v_mov_b32_e32 v29, v2
	v_mov_b32_e32 v34, v2
	v_mov_b32_e32 v35, v2
	v_mov_b32_e32 v36, v2
	v_mov_b32_e32 v37, v2
	v_mov_b32_e32 v42, v2
	v_mov_b32_e32 v43, v2
	v_mov_b32_e32 v44, v2
	v_mov_b32_e32 v45, v2
	v_mov_b32_e32 v50, v2
	v_mov_b32_e32 v51, v2
	v_mov_b32_e32 v52, v2
	v_mov_b32_e32 v53, v2
	v_mov_b32_e32 v14, v2
	v_mov_b32_e32 v15, v2
	v_mov_b32_e32 v16, v2
	v_mov_b32_e32 v17, v2
	v_mov_b32_e32 v22, v2
	v_mov_b32_e32 v23, v2
	v_mov_b32_e32 v24, v2
	v_mov_b32_e32 v25, v2
	v_mov_b32_e32 v30, v2
	v_mov_b32_e32 v31, v2
	v_mov_b32_e32 v32, v2
	v_mov_b32_e32 v33, v2
	v_mov_b32_e32 v38, v2
	v_mov_b32_e32 v39, v2
	v_mov_b32_e32 v40, v2
	v_mov_b32_e32 v41, v2
	v_mov_b32_e32 v46, v2
	v_mov_b32_e32 v47, v2
	v_mov_b32_e32 v48, v2
	v_mov_b32_e32 v49, v2
	v_mov_b32_e32 v54, v2
	v_mov_b32_e32 v55, v2
	v_mov_b32_e32 v56, v2
	v_mov_b32_e32 v57, v2
	v_mov_b32_e32 v58, v2
	v_mov_b32_e32 v59, v2
	v_mov_b32_e32 v60, v2
	v_mov_b32_e32 v61, v2
	v_mov_b32_e32 v62, v2
	v_mov_b32_e32 v63, v2
	v_mov_b32_e32 v64, v2
	v_mov_b32_e32 v65, v2
	v_mov_b32_e32 v66, v2
	v_mov_b32_e32 v67, v2
	v_mov_b32_e32 v68, v2
	v_mov_b32_e32 v69, v2
	v_mov_b32_e32 v70, v2
	v_mov_b32_e32 v71, v2
	v_mov_b32_e32 v72, v2
	v_mov_b32_e32 v73, v2
	v_mov_b32_e32 v74, v2
	v_mov_b32_e32 v75, v2
	v_mov_b32_e32 v76, v2
	v_mov_b32_e32 v77, v2
	v_mov_b32_e32 v82, v2
	v_mov_b32_e32 v83, v2
	v_mov_b32_e32 v84, v2
	v_mov_b32_e32 v85, v2
	v_mov_b32_e32 v90, v2
	v_mov_b32_e32 v91, v2
	v_mov_b32_e32 v92, v2
	v_mov_b32_e32 v93, v2
	v_mov_b32_e32 v98, v2
	v_mov_b32_e32 v99, v2
	v_mov_b32_e32 v100, v2
	v_mov_b32_e32 v101, v2
	v_mov_b32_e32 v106, v2
	v_mov_b32_e32 v107, v2
	v_mov_b32_e32 v108, v2
	v_mov_b32_e32 v109, v2
	v_mov_b32_e32 v114, v2
	v_mov_b32_e32 v115, v2
	v_mov_b32_e32 v116, v2
	v_mov_b32_e32 v117, v2
	v_mov_b32_e32 v78, v2
	v_mov_b32_e32 v79, v2
	v_mov_b32_e32 v80, v2
	v_mov_b32_e32 v81, v2
	v_mov_b32_e32 v86, v2
	v_mov_b32_e32 v87, v2
	v_mov_b32_e32 v88, v2
	v_mov_b32_e32 v89, v2
	v_mov_b32_e32 v94, v2
	v_mov_b32_e32 v95, v2
	v_mov_b32_e32 v96, v2
	v_mov_b32_e32 v97, v2
	v_mov_b32_e32 v102, v2
	v_mov_b32_e32 v103, v2
	v_mov_b32_e32 v104, v2
	v_mov_b32_e32 v105, v2
	v_mov_b32_e32 v110, v2
	v_mov_b32_e32 v111, v2
	v_mov_b32_e32 v112, v2
	v_mov_b32_e32 v113, v2
	v_mov_b32_e32 v118, v2
	v_mov_b32_e32 v119, v2
	v_mov_b32_e32 v120, v2
	v_mov_b32_e32 v121, v2
	v_mov_b32_e32 v122, v2
	v_mov_b32_e32 v123, v2
	v_mov_b32_e32 v124, v2
	v_mov_b32_e32 v125, v2
	v_mov_b32_e32 v126, v2
	v_mov_b32_e32 v127, v2
	v_mov_b32_e32 v128, v2
	v_mov_b32_e32 v129, v2
	.p2align	6

.LBB0_180:
	s_or_b64 exec, exec, s[8:9]
	.p2align	6

.LBB0_539:
	s_ashr_i32 s39, s38, 31
	s_lshl_b64 s[40:41], s[38:39], 21
	s_add_u32 s40, s19, s40
	s_addc_u32 s41, s25, s41
	s_and_b64 s[42:43], s[6:7], exec
	s_cselect_b32 s39, s41, s45
	s_cselect_b32 s66, s40, s44
	s_ashr_i32 s37, s36, 31
	s_lshl_b64 s[42:43], s[36:37], 21
	s_add_u32 s42, s52, s42
	s_addc_u32 s43, s53, s43
	s_and_b64 s[50:51], s[6:7], exec
	s_cselect_b32 s37, s43, s49
	s_cselect_b32 s67, s42, s48
	s_add_u32 s68, s48, 0x100
	v_mov_b32_e32 v2, 0
	v_lshl_add_u32 v138, s46, 8, v1
	v_lshl_or_b32 v140, s47, 8, v187
	v_lshl_add_u64 v[142:143], s[44:45], 0, v[166:167]
	v_lshl_add_u64 v[144:145], s[44:45], 0, v[168:169]
	s_addc_u32 s69, s49, 0
	s_mov_b32 s70, -2
	s_mov_b64 s[46:47], 0
	v_mov_b32_e32 v3, v2
	v_mov_b32_e32 v4, v2
	v_mov_b32_e32 v5, v2
	v_mov_b32_e32 v6, v2
	v_mov_b32_e32 v7, v2
	v_mov_b32_e32 v8, v2
	v_mov_b32_e32 v9, v2
	v_mov_b32_e32 v14, v2
	v_mov_b32_e32 v15, v2
	v_mov_b32_e32 v16, v2
	v_mov_b32_e32 v17, v2
	v_mov_b32_e32 v22, v2
	v_mov_b32_e32 v23, v2
	v_mov_b32_e32 v24, v2
	v_mov_b32_e32 v25, v2
	v_mov_b32_e32 v30, v2
	v_mov_b32_e32 v31, v2
	v_mov_b32_e32 v32, v2
	v_mov_b32_e32 v33, v2
	v_mov_b32_e32 v38, v2
	v_mov_b32_e32 v39, v2
	v_mov_b32_e32 v40, v2
	v_mov_b32_e32 v41, v2
	v_mov_b32_e32 v46, v2
	v_mov_b32_e32 v47, v2
	v_mov_b32_e32 v48, v2
	v_mov_b32_e32 v49, v2
	v_mov_b32_e32 v54, v2
	v_mov_b32_e32 v55, v2
	v_mov_b32_e32 v56, v2
	v_mov_b32_e32 v57, v2
	v_mov_b32_e32 v10, v2
	v_mov_b32_e32 v11, v2
	v_mov_b32_e32 v12, v2
	v_mov_b32_e32 v13, v2
	v_mov_b32_e32 v18, v2
	v_mov_b32_e32 v19, v2
	v_mov_b32_e32 v20, v2
	v_mov_b32_e32 v21, v2
	v_mov_b32_e32 v26, v2
	v_mov_b32_e32 v27, v2
	v_mov_b32_e32 v28, v2
	v_mov_b32_e32 v29, v2
	v_mov_b32_e32 v34, v2
	v_mov_b32_e32 v35, v2
	v_mov_b32_e32 v36, v2
	v_mov_b32_e32 v37, v2
	v_mov_b32_e32 v42, v2
	v_mov_b32_e32 v43, v2
	v_mov_b32_e32 v44, v2
	v_mov_b32_e32 v45, v2
	v_mov_b32_e32 v50, v2
	v_mov_b32_e32 v51, v2
	v_mov_b32_e32 v52, v2
	v_mov_b32_e32 v53, v2
	v_mov_b32_e32 v58, v2
	v_mov_b32_e32 v59, v2
	v_mov_b32_e32 v60, v2
	v_mov_b32_e32 v61, v2
	v_mov_b32_e32 v62, v2
	v_mov_b32_e32 v63, v2
	v_mov_b32_e32 v64, v2
	v_mov_b32_e32 v65, v2
	v_mov_b32_e32 v66, v2
	v_mov_b32_e32 v67, v2
	v_mov_b32_e32 v68, v2
	v_mov_b32_e32 v69, v2
	v_mov_b32_e32 v70, v2
	v_mov_b32_e32 v71, v2
	v_mov_b32_e32 v72, v2
	v_mov_b32_e32 v73, v2
	v_mov_b32_e32 v78, v2
	v_mov_b32_e32 v79, v2
	v_mov_b32_e32 v80, v2
	v_mov_b32_e32 v81, v2
	v_mov_b32_e32 v86, v2
	v_mov_b32_e32 v87, v2
	v_mov_b32_e32 v88, v2
	v_mov_b32_e32 v89, v2
	v_mov_b32_e32 v94, v2
	v_mov_b32_e32 v95, v2
	v_mov_b32_e32 v96, v2
	v_mov_b32_e32 v97, v2
	v_mov_b32_e32 v102, v2
	v_mov_b32_e32 v103, v2
	v_mov_b32_e32 v104, v2
	v_mov_b32_e32 v105, v2
	v_mov_b32_e32 v110, v2
	v_mov_b32_e32 v111, v2
	v_mov_b32_e32 v112, v2
	v_mov_b32_e32 v113, v2
	v_mov_b32_e32 v118, v2
	v_mov_b32_e32 v119, v2
	v_mov_b32_e32 v120, v2
	v_mov_b32_e32 v121, v2
	v_mov_b32_e32 v74, v2
	v_mov_b32_e32 v75, v2
	v_mov_b32_e32 v76, v2
	v_mov_b32_e32 v77, v2
	v_mov_b32_e32 v82, v2
	v_mov_b32_e32 v83, v2
	v_mov_b32_e32 v84, v2
	v_mov_b32_e32 v85, v2
	v_mov_b32_e32 v90, v2
	v_mov_b32_e32 v91, v2
	v_mov_b32_e32 v92, v2
	v_mov_b32_e32 v93, v2
	v_mov_b32_e32 v98, v2
	v_mov_b32_e32 v99, v2
	v_mov_b32_e32 v100, v2
	v_mov_b32_e32 v101, v2
	v_mov_b32_e32 v106, v2
	v_mov_b32_e32 v107, v2
	v_mov_b32_e32 v108, v2
	v_mov_b32_e32 v109, v2
	v_mov_b32_e32 v114, v2
	v_mov_b32_e32 v115, v2
	v_mov_b32_e32 v116, v2
	v_mov_b32_e32 v117, v2
	v_mov_b32_e32 v122, v2
	v_mov_b32_e32 v123, v2
	v_mov_b32_e32 v124, v2
	v_mov_b32_e32 v125, v2
	v_mov_b32_e32 v126, v2
	v_mov_b32_e32 v127, v2
	v_mov_b32_e32 v128, v2
	v_mov_b32_e32 v129, v2
	s_branch .LBB0_541
	.p2align	6

.LBB0_617:
	s_ashr_i32 s39, s38, 31
	s_lshl_b64 s[40:41], s[38:39], 21
	s_add_u32 s40, s35, s40
	s_addc_u32 s41, s52, s41
	s_and_b64 s[42:43], s[8:9], exec
	s_cselect_b32 s39, s41, s47
	s_cselect_b32 s64, s40, s46
	s_ashr_i32 s37, s36, 31
	s_lshl_b64 s[42:43], s[36:37], 21
	s_add_u32 s42, s19, s42
	s_addc_u32 s43, s25, s43
	s_and_b64 s[50:51], s[8:9], exec
	s_cselect_b32 s37, s43, s49
	s_cselect_b32 s65, s42, s48
	s_add_u32 s46, s46, 0x100080
	s_addc_u32 s47, s47, 0
	s_add_u32 s66, s48, 0x100
	v_mov_b32_e32 v2, 0
	s_addc_u32 s67, s49, 0
	s_mov_b32 s68, -2
	v_mov_b32_e32 v3, v2
	v_mov_b32_e32 v4, v2
	v_mov_b32_e32 v5, v2
	v_mov_b32_e32 v6, v2
	v_mov_b32_e32 v7, v2
	v_mov_b32_e32 v8, v2
	v_mov_b32_e32 v9, v2
	v_mov_b32_e32 v10, v2
	v_mov_b32_e32 v11, v2
	v_mov_b32_e32 v12, v2
	v_mov_b32_e32 v13, v2
	v_mov_b32_e32 v18, v2
	v_mov_b32_e32 v19, v2
	v_mov_b32_e32 v20, v2
	v_mov_b32_e32 v21, v2
	v_mov_b32_e32 v26, v2
	v_mov_b32_e32 v27, v2
	v_mov_b32_e32 v28, v2
	v_mov_b32_e32 v29, v2
	v_mov_b32_e32 v34, v2
	v_mov_b32_e32 v35, v2
	v_mov_b32_e32 v36, v2
	v_mov_b32_e32 v37, v2
	v_mov_b32_e32 v46, v2
	v_mov_b32_e32 v47, v2
	v_mov_b32_e32 v48, v2
	v_mov_b32_e32 v49, v2
	v_mov_b32_e32 v54, v2
	v_mov_b32_e32 v55, v2
	v_mov_b32_e32 v56, v2
	v_mov_b32_e32 v57, v2
	v_mov_b32_e32 v14, v2
	v_mov_b32_e32 v15, v2
	v_mov_b32_e32 v16, v2
	v_mov_b32_e32 v17, v2
	v_mov_b32_e32 v22, v2
	v_mov_b32_e32 v23, v2
	v_mov_b32_e32 v24, v2
	v_mov_b32_e32 v25, v2
	v_mov_b32_e32 v30, v2
	v_mov_b32_e32 v31, v2
	v_mov_b32_e32 v32, v2
	v_mov_b32_e32 v33, v2
	v_mov_b32_e32 v38, v2
	v_mov_b32_e32 v39, v2
	v_mov_b32_e32 v40, v2
	v_mov_b32_e32 v41, v2
	v_mov_b32_e32 v42, v2
	v_mov_b32_e32 v43, v2
	v_mov_b32_e32 v44, v2
	v_mov_b32_e32 v45, v2
	v_mov_b32_e32 v50, v2
	v_mov_b32_e32 v51, v2
	v_mov_b32_e32 v52, v2
	v_mov_b32_e32 v53, v2
	v_mov_b32_e32 v58, v2
	v_mov_b32_e32 v59, v2
	v_mov_b32_e32 v60, v2
	v_mov_b32_e32 v61, v2
	v_mov_b32_e32 v62, v2
	v_mov_b32_e32 v63, v2
	v_mov_b32_e32 v64, v2
	v_mov_b32_e32 v65, v2
	v_mov_b32_e32 v66, v2
	v_mov_b32_e32 v67, v2
	v_mov_b32_e32 v68, v2
	v_mov_b32_e32 v69, v2
	v_mov_b32_e32 v70, v2
	v_mov_b32_e32 v71, v2
	v_mov_b32_e32 v72, v2
	v_mov_b32_e32 v73, v2
	v_mov_b32_e32 v74, v2
	v_mov_b32_e32 v75, v2
	v_mov_b32_e32 v76, v2
	v_mov_b32_e32 v77, v2
	v_mov_b32_e32 v82, v2
	v_mov_b32_e32 v83, v2
	v_mov_b32_e32 v84, v2
	v_mov_b32_e32 v85, v2
	v_mov_b32_e32 v90, v2
	v_mov_b32_e32 v91, v2
	v_mov_b32_e32 v92, v2
	v_mov_b32_e32 v93, v2
	v_mov_b32_e32 v94, v2
	v_mov_b32_e32 v95, v2
	v_mov_b32_e32 v96, v2
	v_mov_b32_e32 v97, v2
	v_mov_b32_e32 v106, v2
	v_mov_b32_e32 v107, v2
	v_mov_b32_e32 v108, v2
	v_mov_b32_e32 v109, v2
	v_mov_b32_e32 v110, v2
	v_mov_b32_e32 v111, v2
	v_mov_b32_e32 v112, v2
	v_mov_b32_e32 v113, v2
	v_mov_b32_e32 v78, v2
	v_mov_b32_e32 v79, v2
	v_mov_b32_e32 v80, v2
	v_mov_b32_e32 v81, v2
	v_mov_b32_e32 v86, v2
	v_mov_b32_e32 v87, v2
	v_mov_b32_e32 v88, v2
	v_mov_b32_e32 v89, v2
	v_mov_b32_e32 v98, v2
	v_mov_b32_e32 v99, v2
	v_mov_b32_e32 v100, v2
	v_mov_b32_e32 v101, v2
	v_mov_b32_e32 v102, v2
	v_mov_b32_e32 v103, v2
	v_mov_b32_e32 v104, v2
	v_mov_b32_e32 v105, v2
	v_mov_b32_e32 v114, v2
	v_mov_b32_e32 v115, v2
	v_mov_b32_e32 v116, v2
	v_mov_b32_e32 v117, v2
	v_mov_b32_e32 v118, v2
	v_mov_b32_e32 v119, v2
	v_mov_b32_e32 v120, v2
	v_mov_b32_e32 v121, v2
	v_mov_b32_e32 v122, v2
	v_mov_b32_e32 v123, v2
	v_mov_b32_e32 v124, v2
	v_mov_b32_e32 v125, v2
	v_mov_b32_e32 v126, v2
	v_mov_b32_e32 v127, v2
	v_mov_b32_e32 v128, v2
	v_mov_b32_e32 v129, v2
	.p2align	6

.LBB0_742:
	s_ashr_i32 s61, s60, 31
	s_lshl_b64 s[62:63], s[60:61], 21
	s_add_u32 s62, s17, s62
	s_addc_u32 s63, s19, s63
	s_and_b64 s[64:65], s[14:15], exec
	s_cselect_b32 s61, s63, s71
	s_cselect_b32 s67, s62, s70
	s_ashr_i32 s59, s58, 31
	s_lshl_b64 s[64:65], s[58:59], 21
	s_add_u32 s64, s25, s64
	s_addc_u32 s65, s76, s65
	s_and_b64 s[74:75], s[14:15], exec
	s_cselect_b32 s59, s65, s73
	s_cselect_b32 s69, s64, s72
	s_add_u32 s70, s70, 0x100080
	s_addc_u32 s71, s71, 0
	s_add_u32 s93, s72, 0x100
	v_mov_b32_e32 v26, 0
	s_addc_u32 s94, s73, 0
	s_mov_b32 s95, -2
	v_mov_b32_e32 v27, v26
	v_mov_b32_e32 v28, v26
	v_mov_b32_e32 v29, v26
	v_mov_b32_e32 v30, v26
	v_mov_b32_e32 v31, v26
	v_mov_b32_e32 v32, v26
	v_mov_b32_e32 v33, v26
	v_mov_b32_e32 v18, v26
	v_mov_b32_e32 v19, v26
	v_mov_b32_e32 v20, v26
	v_mov_b32_e32 v21, v26
	v_mov_b32_e32 v22, v26
	v_mov_b32_e32 v23, v26
	v_mov_b32_e32 v24, v26
	v_mov_b32_e32 v25, v26
	v_mov_b32_e32 v10, v26
	v_mov_b32_e32 v11, v26
	v_mov_b32_e32 v12, v26
	v_mov_b32_e32 v13, v26
	v_mov_b32_e32 v14, v26
	v_mov_b32_e32 v15, v26
	v_mov_b32_e32 v16, v26
	v_mov_b32_e32 v17, v26
	v_mov_b32_e32 v2, v26
	v_mov_b32_e32 v3, v26
	v_mov_b32_e32 v4, v26
	v_mov_b32_e32 v5, v26
	v_mov_b32_e32 v6, v26
	v_mov_b32_e32 v7, v26
	v_mov_b32_e32 v8, v26
	v_mov_b32_e32 v9, v26
	v_mov_b32_e32 v90, v26
	v_mov_b32_e32 v91, v26
	v_mov_b32_e32 v92, v26
	v_mov_b32_e32 v93, v26
	v_mov_b32_e32 v94, v26
	v_mov_b32_e32 v95, v26
	v_mov_b32_e32 v96, v26
	v_mov_b32_e32 v97, v26
	v_mov_b32_e32 v82, v26
	v_mov_b32_e32 v83, v26
	v_mov_b32_e32 v84, v26
	v_mov_b32_e32 v85, v26
	v_mov_b32_e32 v86, v26
	v_mov_b32_e32 v87, v26
	v_mov_b32_e32 v88, v26
	v_mov_b32_e32 v89, v26
	v_mov_b32_e32 v74, v26
	v_mov_b32_e32 v75, v26
	v_mov_b32_e32 v76, v26
	v_mov_b32_e32 v77, v26
	v_mov_b32_e32 v78, v26
	v_mov_b32_e32 v79, v26
	v_mov_b32_e32 v80, v26
	v_mov_b32_e32 v81, v26
	v_mov_b32_e32 v66, v26
	v_mov_b32_e32 v67, v26
	v_mov_b32_e32 v68, v26
	v_mov_b32_e32 v69, v26
	v_mov_b32_e32 v70, v26
	v_mov_b32_e32 v71, v26
	v_mov_b32_e32 v72, v26
	v_mov_b32_e32 v73, v26
	v_mov_b32_e32 v58, v26
	v_mov_b32_e32 v59, v26
	v_mov_b32_e32 v60, v26
	v_mov_b32_e32 v61, v26
	v_mov_b32_e32 v62, v26
	v_mov_b32_e32 v63, v26
	v_mov_b32_e32 v64, v26
	v_mov_b32_e32 v65, v26
	v_mov_b32_e32 v50, v26
	v_mov_b32_e32 v51, v26
	v_mov_b32_e32 v52, v26
	v_mov_b32_e32 v53, v26
	v_mov_b32_e32 v54, v26
	v_mov_b32_e32 v55, v26
	v_mov_b32_e32 v56, v26
	v_mov_b32_e32 v57, v26
	v_mov_b32_e32 v42, v26
	v_mov_b32_e32 v43, v26
	v_mov_b32_e32 v44, v26
	v_mov_b32_e32 v45, v26
	v_mov_b32_e32 v46, v26
	v_mov_b32_e32 v47, v26
	v_mov_b32_e32 v48, v26
	v_mov_b32_e32 v49, v26
	v_mov_b32_e32 v34, v26
	v_mov_b32_e32 v35, v26
	v_mov_b32_e32 v36, v26
	v_mov_b32_e32 v37, v26
	v_mov_b32_e32 v38, v26
	v_mov_b32_e32 v39, v26
	v_mov_b32_e32 v40, v26
	v_mov_b32_e32 v41, v26
	v_mov_b32_e32 v122, v26
	v_mov_b32_e32 v123, v26
	v_mov_b32_e32 v124, v26
	v_mov_b32_e32 v125, v26
	v_mov_b32_e32 v126, v26
	v_mov_b32_e32 v127, v26
	v_mov_b32_e32 v128, v26
	v_mov_b32_e32 v129, v26
	v_mov_b32_e32 v114, v26
	v_mov_b32_e32 v115, v26
	v_mov_b32_e32 v116, v26
	v_mov_b32_e32 v117, v26
	v_mov_b32_e32 v118, v26
	v_mov_b32_e32 v119, v26
	v_mov_b32_e32 v120, v26
	v_mov_b32_e32 v121, v26
	v_mov_b32_e32 v106, v26
	v_mov_b32_e32 v107, v26
	v_mov_b32_e32 v108, v26
	v_mov_b32_e32 v109, v26
	v_mov_b32_e32 v110, v26
	v_mov_b32_e32 v111, v26
	v_mov_b32_e32 v112, v26
	v_mov_b32_e32 v113, v26
	v_mov_b32_e32 v98, v26
	v_mov_b32_e32 v99, v26
	v_mov_b32_e32 v100, v26
	v_mov_b32_e32 v101, v26
	v_mov_b32_e32 v102, v26
	v_mov_b32_e32 v103, v26
	v_mov_b32_e32 v104, v26
	v_mov_b32_e32 v105, v26
	.p2align	6

.LBB0_901:
	s_add_u32 s71, s50, 0x100
	v_mov_b32_e32 v0, 0
	s_addc_u32 s72, s51, 0
	s_mov_b32 s73, -2
	v_mov_b32_e32 v1, v0
	v_mov_b32_e32 v2, v0
	v_mov_b32_e32 v3, v0
	v_mov_b32_e32 v4, v0
	v_mov_b32_e32 v5, v0
	v_mov_b32_e32 v6, v0
	v_mov_b32_e32 v7, v0
	v_mov_b32_e32 v16, v0
	v_mov_b32_e32 v17, v0
	v_mov_b32_e32 v18, v0
	v_mov_b32_e32 v19, v0
	v_mov_b32_e32 v20, v0
	v_mov_b32_e32 v21, v0
	v_mov_b32_e32 v22, v0
	v_mov_b32_e32 v23, v0
	v_mov_b32_e32 v32, v0
	v_mov_b32_e32 v33, v0
	v_mov_b32_e32 v34, v0
	v_mov_b32_e32 v35, v0
	v_mov_b32_e32 v36, v0
	v_mov_b32_e32 v37, v0
	v_mov_b32_e32 v38, v0
	v_mov_b32_e32 v39, v0
	v_mov_b32_e32 v48, v0
	v_mov_b32_e32 v49, v0
	v_mov_b32_e32 v50, v0
	v_mov_b32_e32 v51, v0
	v_mov_b32_e32 v52, v0
	v_mov_b32_e32 v53, v0
	v_mov_b32_e32 v54, v0
	v_mov_b32_e32 v55, v0
	v_mov_b32_e32 v8, v0
	v_mov_b32_e32 v9, v0
	v_mov_b32_e32 v10, v0
	v_mov_b32_e32 v11, v0
	v_mov_b32_e32 v12, v0
	v_mov_b32_e32 v13, v0
	v_mov_b32_e32 v14, v0
	v_mov_b32_e32 v15, v0
	v_mov_b32_e32 v24, v0
	v_mov_b32_e32 v25, v0
	v_mov_b32_e32 v26, v0
	v_mov_b32_e32 v27, v0
	v_mov_b32_e32 v28, v0
	v_mov_b32_e32 v29, v0
	v_mov_b32_e32 v30, v0
	v_mov_b32_e32 v31, v0
	v_mov_b32_e32 v40, v0
	v_mov_b32_e32 v41, v0
	v_mov_b32_e32 v42, v0
	v_mov_b32_e32 v43, v0
	v_mov_b32_e32 v44, v0
	v_mov_b32_e32 v45, v0
	v_mov_b32_e32 v46, v0
	v_mov_b32_e32 v47, v0
	v_mov_b32_e32 v56, v0
	v_mov_b32_e32 v57, v0
	v_mov_b32_e32 v58, v0
	v_mov_b32_e32 v59, v0
	v_mov_b32_e32 v60, v0
	v_mov_b32_e32 v61, v0
	v_mov_b32_e32 v62, v0
	v_mov_b32_e32 v63, v0
	v_mov_b32_e32 v64, v0
	v_mov_b32_e32 v65, v0
	v_mov_b32_e32 v66, v0
	v_mov_b32_e32 v67, v0
	v_mov_b32_e32 v68, v0
	v_mov_b32_e32 v69, v0
	v_mov_b32_e32 v70, v0
	v_mov_b32_e32 v71, v0
	v_mov_b32_e32 v80, v0
	v_mov_b32_e32 v81, v0
	v_mov_b32_e32 v82, v0
	v_mov_b32_e32 v83, v0
	v_mov_b32_e32 v84, v0
	v_mov_b32_e32 v85, v0
	v_mov_b32_e32 v86, v0
	v_mov_b32_e32 v87, v0
	v_mov_b32_e32 v96, v0
	v_mov_b32_e32 v97, v0
	v_mov_b32_e32 v98, v0
	v_mov_b32_e32 v99, v0
	v_mov_b32_e32 v100, v0
	v_mov_b32_e32 v101, v0
	v_mov_b32_e32 v102, v0
	v_mov_b32_e32 v103, v0
	v_mov_b32_e32 v104, v0
	v_mov_b32_e32 v105, v0
	v_mov_b32_e32 v106, v0
	v_mov_b32_e32 v107, v0
	v_mov_b32_e32 v108, v0
	v_mov_b32_e32 v109, v0
	v_mov_b32_e32 v110, v0
	v_mov_b32_e32 v111, v0
	v_mov_b32_e32 v72, v0
	v_mov_b32_e32 v73, v0
	v_mov_b32_e32 v74, v0
	v_mov_b32_e32 v75, v0
	v_mov_b32_e32 v76, v0
	v_mov_b32_e32 v77, v0
	v_mov_b32_e32 v78, v0
	v_mov_b32_e32 v79, v0
	v_mov_b32_e32 v88, v0
	v_mov_b32_e32 v89, v0
	v_mov_b32_e32 v90, v0
	v_mov_b32_e32 v91, v0
	v_mov_b32_e32 v92, v0
	v_mov_b32_e32 v93, v0
	v_mov_b32_e32 v94, v0
	v_mov_b32_e32 v95, v0
	v_mov_b32_e32 v112, v0
	v_mov_b32_e32 v113, v0
	v_mov_b32_e32 v114, v0
	v_mov_b32_e32 v115, v0
	v_mov_b32_e32 v116, v0
	v_mov_b32_e32 v117, v0
	v_mov_b32_e32 v118, v0
	v_mov_b32_e32 v119, v0
	v_mov_b32_e32 v120, v0
	v_mov_b32_e32 v121, v0
	v_mov_b32_e32 v122, v0
	v_mov_b32_e32 v123, v0
	v_mov_b32_e32 v124, v0
	v_mov_b32_e32 v125, v0
	v_mov_b32_e32 v126, v0
	v_mov_b32_e32 v127, v0
	.p2align	6
